# final-phase loads batched and DPP/permlane row sums; SSM discretization moved to otherwise idle blocks; on top of v22
# baseline (speedup 1.0000x reference)
; DI float wave_sum(float v) {
; #pragma unroll
;   for (int o = 32; o > 0; o >>= 1) v += __shfl_xor(v, o);
;   return v;
; }
; __device__ void phase_final(const Params& p) {
;     ...
;   for (int R0 = gw; R0 < NTOK; R0 += 2 * nw) {
;     const int Rr[2] = {R0, R0 + nw < NTOK ? R0 + nw : R0};
;     float4 v[2][4];
;     float ss[2] = {0.f, 0.f};
; #pragma unroll
;     for (int r = 0; r < 2; ++r)
; #pragma unroll
;       for (int i = 0; i < 4; ++i) v[r][i] = *reinterpret_cast<const float4*>(p.out + (size_t)Rr[r] * 1024 + i * 256 + lane * 4);
; #pragma unroll
;     for (int r = 0; r < 2; ++r) {
; #pragma unroll
;       for (int i = 0; i < 4; ++i) ss[r] += v[r][i].x * v[r][i].x + v[r][i].y * v[r][i].y + v[r][i].z * v[r][i].z + v[r][i].w * v[r][i].w;
;       ss[r] = wave_sum(ss[r]);
;     }
; #pragma unroll
;     for (int r = 0; r < 2; ++r) {
;       if (r == 1 && R0 + nw >= NTOK) break;
;       const float rstd = rsqrtf(ss[r] * (1.f / 1024.f) + 1e-6f);
; #pragma unroll
;       for (int i = 0; i < 4; ++i) {
;         float4 o;
;         o.x = v[r][i].x * rstd * g4[i].x; o.y = v[r][i].y * rstd * g4[i].y; o.z = v[r][i].z * rstd * g4[i].z; o.w = v[r][i].w * rstd * g4[i].w;
;         *reinterpret_cast<float4*>(p.out + (size_t)Rr[r] * 1024 + i * 256 + lane * 4) = o;
;       }
;     }
.LBB0_20:
	v_ashrrev_i32_e32 v19, 31, v18
	v_lshlrev_b64 v[20:21], 12, v[18:19]
	v_lshl_add_u64 v[36:37], v[34:35], 0, v[20:21]
	global_load_dwordx4 v[48:51], v[36:37], off
	global_load_dwordx4 v[52:55], v[36:37], off offset:1024
	global_load_dwordx4 v[56:59], v[36:37], off offset:2048
	global_load_dwordx4 v[60:63], v[36:37], off offset:3072
	v_add_u32_e32 v0, s17, v18
	s_mov_b32 s0, 0x10200
	v_cmp_gt_i32_e32 vcc, s0, v0
	s_mov_b32 s0, 0x800000
	s_nop 0
	v_cndmask_b32_e32 v18, v18, v0, vcc
	v_ashrrev_i32_e32 v19, 31, v18
	v_lshlrev_b64 v[18:19], 12, v[18:19]
	v_lshl_add_u64 v[38:39], v[34:35], 0, v[18:19]
	global_load_dwordx4 v[30:33], v[38:39], off
	global_load_dwordx4 v[26:29], v[38:39], off offset:1024
	global_load_dwordx4 v[22:25], v[38:39], off offset:2048
	global_load_dwordx4 v[18:21], v[38:39], off offset:3072
	s_waitcnt vmcnt(4)
	v_mov_b32_e32 v64, v49
	v_mov_b32_e32 v65, v53
	v_mov_b32_e32 v46, v48
	v_mov_b32_e32 v47, v52
	v_mov_b32_e32 v72, v57
	v_mov_b32_e32 v73, v61
	v_pk_mul_f32 v[64:65], v[64:65], v[64:65]
	v_mov_b32_e32 v66, v50
	v_mov_b32_e32 v67, v54
	v_mov_b32_e32 v70, v56
	v_mov_b32_e32 v71, v60
	v_pk_mul_f32 v[72:73], v[72:73], v[72:73]
	v_pk_fma_f32 v[46:47], v[46:47], v[46:47], v[64:65]
	v_mov_b32_e32 v68, v51
	v_mov_b32_e32 v69, v55
	v_mov_b32_e32 v74, v58
	v_mov_b32_e32 v75, v62
	v_pk_fma_f32 v[64:65], v[70:71], v[70:71], v[72:73]
	v_pk_fma_f32 v[46:47], v[66:67], v[66:67], v[46:47]
	v_mov_b32_e32 v76, v59
	v_mov_b32_e32 v77, v63
	v_pk_fma_f32 v[64:65], v[74:75], v[74:75], v[64:65]
	v_pk_fma_f32 v[46:47], v[68:69], v[68:69], v[46:47]
	v_pk_fma_f32 v[64:65], v[76:77], v[76:77], v[64:65]
	v_add_f32_e32 v46, v46, v47
	v_add_f32_e32 v46, v46, v64
	v_add_f32_e32 v46, v46, v65
	s_nop 1
	v_add_f32_dpp v46, v46, v46 quad_perm:[1,0,3,2] row_mask:0xf bank_mask:0xf
	s_nop 1
	v_add_f32_dpp v46, v46, v46 quad_perm:[2,3,0,1] row_mask:0xf bank_mask:0xf
	s_nop 1
	v_add_f32_dpp v46, v46, v46 row_half_mirror row_mask:0xf bank_mask:0xf
	s_nop 1
	v_add_f32_dpp v46, v46, v46 row_mirror row_mask:0xf bank_mask:0xf
	s_nop 1
	v_mov_b32_e32 v47, v46
	s_nop 1
	v_permlane16_swap_b32_e32 v47, v46
	v_add_f32_e32 v46, v46, v47
	v_mov_b32_e32 v47, v46
	s_nop 1
	v_permlane32_swap_b32_e32 v47, v46
	v_add_f32_e32 v46, v46, v47
	v_fmamk_f32 v46, v46, 0x3a800000, v155
	v_mul_f32_e32 v47, 0x4b800000, v46
	v_cmp_gt_f32_e64 s[0:1], s0, v46
	s_waitcnt vmcnt(0)
	v_pk_mul_f32 v[70:71], v[30:31], v[30:31]
	v_pk_mul_f32 v[78:79], v[26:27], v[26:27]
	v_pk_mul_f32 v[72:73], v[32:33], v[32:33]
	v_pk_mul_f32 v[80:81], v[28:29], v[28:29]
	v_pk_mul_f32 v[82:83], v[22:23], v[22:23]
	v_add_f32_e32 v66, v78, v79
	v_add_f32_e32 v67, v70, v71
	v_pk_mul_f32 v[84:85], v[24:25], v[24:25]
	v_pk_mul_f32 v[86:87], v[18:19], v[18:19]
	v_add_f32_e32 v70, v82, v83
	v_add_f32_e32 v66, v66, v80
	v_add_f32_e32 v67, v67, v72
	v_pk_mul_f32 v[88:89], v[20:21], v[20:21]
	v_add_f32_e32 v71, v86, v87
	v_add_f32_e32 v68, v70, v84
	v_add_f32_e32 v64, v66, v81
	v_add_f32_e32 v65, v67, v73
	v_add_f32_e32 v69, v71, v88
	v_add_f32_e32 v66, v68, v85
	v_add_f32_e32 v64, v65, v64
	v_add_f32_e32 v67, v69, v89
	v_add_f32_e32 v64, v64, v66
	v_add_f32_e32 v64, v64, v67
	v_cndmask_b32_e64 v46, v46, v47, s[0:1]
	v_rsq_f32_e32 v66, v46
	s_nop 1
	v_add_f32_dpp v64, v64, v64 quad_perm:[1,0,3,2] row_mask:0xf bank_mask:0xf
	s_nop 1
	v_add_f32_dpp v64, v64, v64 quad_perm:[2,3,0,1] row_mask:0xf bank_mask:0xf
	s_nop 1
	v_add_f32_dpp v64, v64, v64 row_half_mirror row_mask:0xf bank_mask:0xf
	s_nop 1
	v_add_f32_dpp v64, v64, v64 row_mirror row_mask:0xf bank_mask:0xf
	s_nop 1
	v_mov_b32_e32 v65, v64
	s_nop 1
	v_permlane16_swap_b32_e32 v65, v64
	v_add_f32_e32 v64, v64, v65
	v_mov_b32_e32 v65, v64
	s_nop 1
	v_permlane32_swap_b32_e32 v65, v64
	v_add_f32_e32 v64, v64, v65
	v_mov_b32_e32 v46, v64
	v_mov_b32_e32 v47, 0
	v_mul_f32_e32 v64, 0x45800000, v66
	v_cndmask_b32_e64 v64, v66, v64, s[0:1]
	v_pk_mul_f32 v[48:49], v[48:49], v[64:65] op_sel_hi:[1,0]
	v_pk_mul_f32 v[50:51], v[50:51], v[64:65] op_sel_hi:[1,0]
	v_pk_mul_f32 v[52:53], v[52:53], v[64:65] op_sel_hi:[1,0]
	v_pk_mul_f32 v[54:55], v[54:55], v[64:65] op_sel_hi:[1,0]
	v_pk_mul_f32 v[56:57], v[56:57], v[64:65] op_sel_hi:[1,0]
	v_pk_mul_f32 v[58:59], v[58:59], v[64:65] op_sel_hi:[1,0]
	v_pk_mul_f32 v[60:61], v[60:61], v[64:65] op_sel_hi:[1,0]
	v_pk_mul_f32 v[62:63], v[62:63], v[64:65] op_sel_hi:[1,0]
	v_pk_mul_f32 v[48:49], v[2:3], v[48:49]
	v_pk_mul_f32 v[50:51], v[4:5], v[50:51]
	v_pk_mul_f32 v[52:53], v[6:7], v[52:53]
	v_pk_mul_f32 v[54:55], v[8:9], v[54:55]
	v_pk_mul_f32 v[56:57], v[10:11], v[56:57]
	v_pk_mul_f32 v[58:59], v[12:13], v[58:59]
	v_pk_mul_f32 v[60:61], v[14:15], v[60:61]
	v_pk_mul_f32 v[62:63], v[16:17], v[62:63]
	global_store_dwordx4 v[36:37], v[48:51], off
	global_store_dwordx4 v[36:37], v[52:55], off offset:1024
	global_store_dwordx4 v[36:37], v[56:59], off offset:2048
	global_store_dwordx4 v[36:37], v[60:63], off offset:3072
	s_and_saveexec_b64 s[0:1], vcc
	s_cbranch_execz .LBB0_19
	s_waitcnt lgkmcnt(0)
	v_add_f32_e32 v36, v46, v47
	v_fmamk_f32 v36, v36, 0x3a800000, v155
	s_mov_b32 s8, 0x800000
	v_mul_f32_e32 v37, 0x4b800000, v36
	v_cmp_gt_f32_e32 vcc, s8, v36
	s_nop 1
	v_cndmask_b32_e32 v36, v36, v37, vcc
	v_rsq_f32_e32 v36, v36
	s_nop 0
	v_mul_f32_e32 v37, 0x45800000, v36
	v_cndmask_b32_e32 v36, v36, v37, vcc
	v_pk_mul_f32 v[30:31], v[30:31], v[36:37] op_sel_hi:[1,0]
	v_pk_mul_f32 v[32:33], v[32:33], v[36:37] op_sel_hi:[1,0]
	v_pk_mul_f32 v[26:27], v[26:27], v[36:37] op_sel_hi:[1,0]
	v_pk_mul_f32 v[28:29], v[28:29], v[36:37] op_sel_hi:[1,0]
	v_pk_mul_f32 v[22:23], v[22:23], v[36:37] op_sel_hi:[1,0]
	v_pk_mul_f32 v[24:25], v[24:25], v[36:37] op_sel_hi:[1,0]
	v_pk_mul_f32 v[18:19], v[18:19], v[36:37] op_sel_hi:[1,0]
	v_pk_mul_f32 v[20:21], v[20:21], v[36:37] op_sel_hi:[1,0]
	v_pk_mul_f32 v[30:31], v[2:3], v[30:31]
	v_pk_mul_f32 v[32:33], v[4:5], v[32:33]
	v_pk_mul_f32 v[26:27], v[6:7], v[26:27]
	v_pk_mul_f32 v[28:29], v[8:9], v[28:29]
	v_pk_mul_f32 v[22:23], v[10:11], v[22:23]
	v_pk_mul_f32 v[24:25], v[12:13], v[24:25]
	v_pk_mul_f32 v[18:19], v[14:15], v[18:19]
	v_pk_mul_f32 v[20:21], v[16:17], v[20:21]
	global_store_dwordx4 v[38:39], v[30:33], off
	global_store_dwordx4 v[38:39], v[26:29], off offset:1024
	global_store_dwordx4 v[38:39], v[22:25], off offset:2048
	global_store_dwordx4 v[38:39], v[18:21], off offset:3072
	s_branch .LBB0_19

; __device__ void phase_prep(const Params& p, char* lds) {
;     ...
;   for (int idx = gtid; idx < 2 * 32 * 64; idx += gstride) {
;     const int lg = idx >> 6, pp = idx & 63;
;     const float are = p.a_re[idx], aim = p.a_im[idx];
;     const float dt = expf(p.log_dt[lg]);
;     const float mag = expf(are * dt), ang = aim * dt;
;     const float kk = rintf(ang * 0.15915494309189535f);
;     float r = fmaf(-kk, 6.2831854820251465f, ang);
;     r = fmaf(-kk, -1.7484556e-07f, r);
;     const float cs = cosf(r), sn = sinf(r);
;     const float abr = mag * cs, abi = mag * sn;
;     const float den = are * are + aim * aim;
;     const float nr = abr - 1.f, ni = abi;
;     const float fre = (nr * are + ni * aim) / den, fim = (ni * are - nr * aim) / den;
;     ((float*)(p.ws + WS_ab))[idx * 2] = abr; ((float*)(p.ws + WS_ab))[idx * 2 + 1] = abi;
.LBB0_1576:
	v_add_u32_e32 v2, 0xffff0000, v2
	v_cmp_gt_u32_e32 vcc, s41, v2
	s_and_saveexec_b64 s[6:7], vcc
	v_readlane_b32 s48, v234, 22
	v_readlane_b32 s50, v234, 24
	v_readlane_b32 s52, v234, 26
	s_mov_b32 s4, 0x3fb8aa3b
	s_mov_b32 s5, 0xc2ce8ed0
	s_mov_b32 s20, 0x42b17218
	v_readlane_b32 s49, v234, 23
	v_readlane_b32 s51, v234, 25
	v_readlane_b32 s53, v234, 27
	s_cbranch_execz .LBB0_1587
	v_and_b32_e32 v20, 63, v3
	v_lshlrev_b32_e32 v0, 2, v20
	v_lshl_add_u64 v[6:7], s[36:37], 0, v[0:1]
	s_mov_b64 s[0:1], 0x3586e000
	s_add_u32 s8, s36, 0x2010000
	v_lshl_add_u64 v[4:5], v[6:7], 0, s[0:1]
	s_mov_b64 s[0:1], 0x3586f000
	v_lshlrev_b32_e32 v0, 1, v20
	s_addc_u32 s9, s37, 0
	v_lshl_add_u64 v[6:7], v[6:7], 0, s[0:1]
	v_lshl_add_u64 v[12:13], s[36:37], 0, v[0:1]
	s_mov_b64 s[0:1], 0x2058000
	s_add_u32 s10, s36, 0x2018000
	v_lshl_add_u64 v[10:11], v[12:13], 0, s[0:1]
	s_mov_b64 s[0:1], 0x2058080
	s_addc_u32 s11, s37, 0
	v_lshl_add_u64 v[12:13], v[12:13], 0, s[0:1]
	v_readlane_b32 s0, v236, 36
	s_add_u32 s12, s36, 0x2018800
	s_addc_u32 s13, s37, 0
	s_sub_i32 s0, s0, 0x20000
	v_lshl_add_u32 v14, v3, 1, s0
	v_ashrrev_i32_e32 v3, 31, v2
	v_lshlrev_b32_e32 v8, 5, v20
	v_lshlrev_b64 v[16:17], 6, v[2:3]
	v_lshlrev_b64 v[18:19], 2, v[2:3]
	s_mov_b64 s[14:15], 0
	v_lshlrev_b32_e32 v3, 2, v20
	s_branch .LBB0_1579
